# attention main loops: per-tile wait vmcnt(0) -> vmcnt(2): only the K tile must land before the barrier, the V tile (needed a step later) keeps flying
# speedup vs baseline: 1.0070x; 1.0070x over previous
.LBB0_1031:
	s_lshl_b32 s0, s75, 13
	s_add_i32 s77, s0, 0
	s_setprio 1
	v_add_u32_e32 v112, s77, v189
	v_add_u32_e32 v68, v112, v191
	ds_read_b128 v[64:67], v68 offset:49152
	ds_read_b128 v[68:71], v68 offset:53248
	v_add_u32_e32 v113, v112, v192
	ds_read_b128 v[220:223], v113 offset:49152
	ds_read_b128 v[224:227], v113 offset:53248
	v_add_u32_e32 v113, v112, v193
	s_waitcnt lgkmcnt(0)
	v_mfma_f32_32x32x16_bf16 v[80:95], v[64:67], v[108:111], 0
	v_add_u32_e32 v112, v112, v194
	v_mfma_f32_32x32x16_bf16 v[64:79], v[68:71], v[108:111], 0
	v_mfma_f32_32x32x16_bf16 v[80:95], v[220:223], v[104:107], v[80:95]
	v_mfma_f32_32x32x16_bf16 v[64:79], v[224:227], v[104:107], v[64:79]
	ds_read_b128 v[220:223], v113 offset:49152
	ds_read_b128 v[224:227], v113 offset:53248
	s_waitcnt lgkmcnt(0)
	v_mfma_f32_32x32x16_bf16 v[80:95], v[220:223], v[100:103], v[80:95]
	v_mfma_f32_32x32x16_bf16 v[64:79], v[224:227], v[100:103], v[64:79]
	ds_read_b128 v[220:223], v112 offset:49152
	ds_read_b128 v[224:227], v112 offset:53248
	s_waitcnt lgkmcnt(0)
	v_mfma_f32_32x32x16_bf16 v[80:95], v[220:223], v[96:99], v[80:95]
	v_mfma_f32_32x32x16_bf16 v[64:79], v[224:227], v[96:99], v[64:79]
	s_setprio 0
	v_exp_f32_e32 v174, v174
	v_exp_f32_e32 v175, v175
	v_add_f32_e32 v112, v115, v174
	v_add_f32_e32 v113, v124, v175
	v_exp_f32_e32 v172, v172
	v_add_f32_e32 v112, v112, v125
	v_add_f32_e32 v113, v113, v126
	v_exp_f32_e32 v173, v173
	v_add_f32_e32 v112, v112, v172
	v_add_f32_e32 v113, v113, v173
	v_exp_f32_e32 v170, v170
	v_add_f32_e32 v112, v112, v127
	v_add_f32_e32 v113, v113, v176
	v_exp_f32_e32 v171, v171
	v_add_f32_e32 v112, v112, v170
	v_add_f32_e32 v113, v113, v171
	v_exp_f32_e32 v168, v168
	v_add_f32_e32 v112, v112, v177
	v_add_f32_e32 v113, v113, v178
	v_exp_f32_e32 v169, v169
	v_add_f32_e32 v112, v112, v168
	v_add_f32_e32 v113, v113, v169
	v_exp_f32_e32 v166, v166
	v_add_f32_e32 v112, v112, v116
	v_add_f32_e32 v113, v113, v117
	v_exp_f32_e32 v167, v167
	v_add_f32_e32 v112, v112, v166
	v_add_f32_e32 v113, v113, v167
	v_exp_f32_e32 v164, v164
	v_add_f32_e32 v112, v112, v118
	v_add_f32_e32 v113, v113, v119
	v_exp_f32_e32 v165, v165
	v_add_f32_e32 v112, v112, v164
	v_add_f32_e32 v113, v113, v165
	v_exp_f32_e32 v162, v162
	v_add_f32_e32 v112, v112, v120
	v_add_f32_e32 v113, v113, v121
	v_exp_f32_e32 v163, v163
	v_exp_f32_e32 v160, v160
	v_exp_f32_e32 v161, v161
	v_add_f32_e32 v112, v112, v162
	v_add_f32_e32 v113, v113, v163
	s_nop 0
	v_add_f32_e32 v112, v112, v122
	v_add_f32_e32 v113, v113, v123
	s_nop 0
	v_add_f32_e32 v112, v112, v160
	v_add_f32_e32 v113, v113, v161
	s_nop 0
	v_add_f32_e32 v219, v112, v113
	v_cvt_pk_bf16_f32 v112, v115, v124
	v_cvt_pk_bf16_f32 v113, v125, v126
	v_cvt_pk_bf16_f32 v114, v127, v176
	v_cvt_pk_bf16_f32 v115, v177, v178
	v_cvt_pk_bf16_f32 v116, v116, v117
	s_nop 0
	v_mov_b32_e32 v220, v219
	s_nop 1
	v_permlane32_swap_b32_e32 v219, v220
	v_cvt_pk_bf16_f32 v117, v118, v119
	v_cvt_pk_bf16_f32 v118, v120, v121
	v_cvt_pk_bf16_f32 v119, v122, v123
	v_cvt_pk_bf16_f32 v120, v174, v175
	v_cvt_pk_bf16_f32 v121, v172, v173
	v_cvt_pk_bf16_f32 v122, v170, v171
	v_cvt_pk_bf16_f32 v123, v168, v169
	v_cvt_pk_bf16_f32 v124, v166, v167
	v_cvt_pk_bf16_f32 v125, v164, v165
	v_cvt_pk_bf16_f32 v126, v162, v163
	v_cvt_pk_bf16_f32 v127, v160, v161
	v_permlane32_swap_b32_e32 v112, v114
	v_permlane32_swap_b32_e32 v113, v115
	v_permlane32_swap_b32_e32 v116, v118
	v_permlane32_swap_b32_e32 v117, v119
	v_permlane32_swap_b32_e32 v120, v122
	v_permlane32_swap_b32_e32 v121, v123
	v_permlane32_swap_b32_e32 v124, v126
	v_permlane32_swap_b32_e32 v125, v127
	s_lshl_b32 s0, s76, 14
	v_add_u32_e32 v176, s0, v187
	ds_read_b64_tr_b16 v[160:161], v176 offset:0
	ds_read_b64_tr_b16 v[162:163], v176 offset:0x800
	ds_read_b64_tr_b16 v[164:165], v176 offset:0x1000
	ds_read_b64_tr_b16 v[166:167], v176 offset:0x1800
	ds_read_b64_tr_b16 v[168:169], v176 offset:0x2000
	ds_read_b64_tr_b16 v[170:171], v176 offset:0x2800
	ds_read_b64_tr_b16 v[172:173], v176 offset:0x3000
	ds_read_b64_tr_b16 v[174:175], v176 offset:0x3800
	s_setprio 1
	s_waitcnt lgkmcnt(6)
	v_mfma_f32_32x32x16_bf16 v[48:63], v[112:115], v[160:163], v[48:63]
	s_waitcnt lgkmcnt(4)
	v_mfma_f32_32x32x16_bf16 v[48:63], v[116:119], v[164:167], v[48:63]
	s_waitcnt lgkmcnt(2)
	v_mfma_f32_32x32x16_bf16 v[48:63], v[120:123], v[168:171], v[48:63]
	s_waitcnt lgkmcnt(0)
	v_mfma_f32_32x32x16_bf16 v[48:63], v[124:127], v[172:175], v[48:63]
	s_setprio 0
	v_max3_f32 v160, v80, v81, v82
	v_max3_f32 v161, v64, v65, v66
	v_max_f32_e32 v162, v79, v79
	v_max3_f32 v160, v160, v83, v84
	v_max3_f32 v161, v161, v67, v68
	v_max_f32_e32 v163, v95, v95
	v_max3_f32 v160, v160, v85, v86
	v_max3_f32 v161, v161, v69, v70
	v_max_f32_e32 v162, v163, v162
	v_max3_f32 v160, v160, v87, v88
	v_max3_f32 v161, v161, v71, v72
	s_nop 0
	v_max3_f32 v160, v160, v89, v90
	v_max3_f32 v161, v161, v73, v74
	s_nop 0
	v_max3_f32 v160, v160, v91, v92
	v_max3_f32 v161, v161, v75, v76
	s_nop 0
	v_max3_f32 v160, v160, v93, v94
	v_max3_f32 v161, v161, v77, v78
	s_nop 0
	v_max3_f32 v160, v160, v161, v162
	s_nop 0
	v_mov_b32_e32 v161, v160
	s_nop 1
	v_permlane32_swap_b32_e32 v160, v161
	v_max_f32_e32 v161, v161, v161
	v_max_f32_e32 v160, v160, v160
	v_max_f32_e32 v177, v160, v161
	ds_read_b64_tr_b16 v[160:161], v176 offset:0x200
	ds_read_b64_tr_b16 v[162:163], v176 offset:0xa00
	ds_read_b64_tr_b16 v[164:165], v176 offset:0x1200
	ds_read_b64_tr_b16 v[166:167], v176 offset:0x1a00
	ds_read_b64_tr_b16 v[168:169], v176 offset:0x2200
	ds_read_b64_tr_b16 v[170:171], v176 offset:0x2a00
	ds_read_b64_tr_b16 v[172:173], v176 offset:0x3200
	ds_read_b64_tr_b16 v[174:175], v176 offset:0x3a00
	s_setprio 1
	s_waitcnt lgkmcnt(6)
	v_mfma_f32_32x32x16_bf16 v[32:47], v[112:115], v[160:163], v[32:47]
	s_waitcnt lgkmcnt(4)
	v_mfma_f32_32x32x16_bf16 v[32:47], v[116:119], v[164:167], v[32:47]
	s_waitcnt lgkmcnt(2)
	v_mfma_f32_32x32x16_bf16 v[32:47], v[120:123], v[168:171], v[32:47]
	s_waitcnt lgkmcnt(0)
	v_mfma_f32_32x32x16_bf16 v[32:47], v[124:127], v[172:175], v[32:47]
	s_setprio 0
	v_sub_f32_e32 v160, v177, v218
	v_cmp_ge_f32_e32 vcc, s71, v160
	v_max_f32_e32 v160, v218, v218
	v_max_f32_e32 v160, v160, v177
	v_sub_f32_e32 v161, v218, v160
	v_mul_f32_e32 v161, 0x3e38aa3b, v161
	v_exp_f32_e32 v161, v161
	s_cmp_eq_u64 vcc, exec
	s_cselect_b64 vcc, -1, 0
	v_cndmask_b32_e32 v222, v160, v218, vcc
	v_cndmask_b32_e64 v221, v161, 1.0, vcc
	v_mul_f32_e32 v175, 0xbe38aa3b, v222
	v_fma_f32 v80, v80, v197, v175
	v_fma_f32 v81, v81, v197, v175
	v_fma_f32 v82, v82, v197, v175
	v_fma_f32 v83, v83, v197, v175
	v_fma_f32 v84, v84, v197, v175
	v_fma_f32 v85, v85, v197, v175
	v_fma_f32 v86, v86, v197, v175
	v_fma_f32 v87, v87, v197, v175
	v_fma_f32 v88, v88, v197, v175
	v_fma_f32 v89, v89, v197, v175
	v_fma_f32 v90, v90, v197, v175
	v_fma_f32 v91, v91, v197, v175
	v_fma_f32 v92, v92, v197, v175
	v_fma_f32 v93, v93, v197, v175
	v_fma_f32 v94, v94, v197, v175
	v_fma_f32 v95, v95, v197, v175
	v_fma_f32 v160, v64, v197, v175
	v_fma_f32 v161, v65, v197, v175
	v_fma_f32 v162, v66, v197, v175
	v_fma_f32 v163, v67, v197, v175
	v_fma_f32 v164, v68, v197, v175
	v_fma_f32 v165, v69, v197, v175
	v_fma_f32 v166, v70, v197, v175
	v_fma_f32 v167, v71, v197, v175
	v_fma_f32 v168, v72, v197, v175
	v_fma_f32 v169, v73, v197, v175
	v_fma_f32 v170, v74, v197, v175
	v_fma_f32 v171, v75, v197, v175
	v_fma_f32 v172, v76, v197, v175
	v_fma_f32 v173, v77, v197, v175
	v_fma_f32 v174, v78, v197, v175
	v_fma_f32 v175, v79, v197, v175
	ds_read_b64_tr_b16 v[64:65], v176 offset:0x400
	ds_read_b64_tr_b16 v[66:67], v176 offset:0xc00
	ds_read_b64_tr_b16 v[68:69], v176 offset:0x1400
	ds_read_b64_tr_b16 v[70:71], v176 offset:0x1c00
	ds_read_b64_tr_b16 v[72:73], v176 offset:0x2400
	ds_read_b64_tr_b16 v[74:75], v176 offset:0x2c00
	ds_read_b64_tr_b16 v[76:77], v176 offset:0x3400
	ds_read_b64_tr_b16 v[78:79], v176 offset:0x3c00
	s_setprio 1
	s_waitcnt lgkmcnt(6)
	v_mfma_f32_32x32x16_bf16 v[16:31], v[112:115], v[64:67], v[16:31]
	s_waitcnt lgkmcnt(4)
	v_mfma_f32_32x32x16_bf16 v[16:31], v[116:119], v[68:71], v[16:31]
	s_waitcnt lgkmcnt(2)
	v_mfma_f32_32x32x16_bf16 v[16:31], v[120:123], v[72:75], v[16:31]
	s_waitcnt lgkmcnt(0)
	v_mfma_f32_32x32x16_bf16 v[16:31], v[124:127], v[76:79], v[16:31]
	s_setprio 0
	ds_read_b64_tr_b16 v[64:65], v176 offset:0x600
	ds_read_b64_tr_b16 v[66:67], v176 offset:0xe00
	ds_read_b64_tr_b16 v[68:69], v176 offset:0x1600
	ds_read_b64_tr_b16 v[70:71], v176 offset:0x1e00
	ds_read_b64_tr_b16 v[72:73], v176 offset:0x2600
	ds_read_b64_tr_b16 v[74:75], v176 offset:0x2e00
	ds_read_b64_tr_b16 v[76:77], v176 offset:0x3600
	ds_read_b64_tr_b16 v[78:79], v176 offset:0x3e00
	s_setprio 1
	s_waitcnt lgkmcnt(6)
	v_mfma_f32_32x32x16_bf16 v[0:15], v[112:115], v[64:67], v[0:15]
	s_waitcnt lgkmcnt(4)
	v_mfma_f32_32x32x16_bf16 v[0:15], v[116:119], v[68:71], v[0:15]
	s_waitcnt lgkmcnt(2)
	v_mfma_f32_32x32x16_bf16 v[0:15], v[120:123], v[72:75], v[0:15]
	s_waitcnt lgkmcnt(0)
	v_mfma_f32_32x32x16_bf16 v[0:15], v[124:127], v[76:79], v[0:15]
	s_setprio 0
	s_lshl_b32 s1, s76, 13
	v_lshl_add_u64 v[176:177], s[46:47], 0, v[154:155]
	s_mov_b64 s[48:49], 0x14210800
	s_add_i32 s1, s51, s1
	s_waitcnt vmcnt(2)
	s_barrier
	v_lshl_add_u64 v[64:65], v[176:177], 0, s[48:49]
	s_add_i32 m0, s1, 0xc000
	v_lshl_add_u64 v[178:179], s[46:47], 0, v[156:157]
	s_add_i32 s0, s51, s0
	global_load_lds_dwordx4 v[64:65], off
	v_lshl_add_u64 v[64:65], v[178:179], 0, s[10:11]
	s_mov_b32 m0, s0
	v_lshl_add_u64 v[180:181], s[46:47], 0, v[158:159]
	global_load_lds_dwordx4 v[64:65], off
	v_lshl_add_u64 v[64:65], v[180:181], 0, s[10:11]
	s_add_i32 m0, s0, 0x2000
	v_cmp_gt_f32_e32 vcc, 1.0, v221
	global_load_lds_dwordx4 v[64:65], off
	s_cbranch_vccz .LBB0_1035
	s_and_saveexec_b64 s[0:1], s[4:5]
	ds_write_b32 v215, v221 offset:128
	s_or_b64 exec, exec, s[0:1]
	s_waitcnt lgkmcnt(0)
	v_add_u32_e32 v76, s50, v188
	ds_read_b128 v[64:67], v76 offset:224
	ds_read_b128 v[68:71], v76 offset:192
	ds_read_b128 v[72:75], v76 offset:160
	ds_read_b128 v[76:79], v76 offset:128
	s_waitcnt lgkmcnt(0)
	v_pk_mul_f32 v[60:61], v[60:61], v[64:65]
	v_pk_mul_f32 v[56:57], v[56:57], v[68:69]
	v_pk_mul_f32 v[52:53], v[52:53], v[72:73]
	v_pk_mul_f32 v[62:63], v[62:63], v[66:67]
	v_pk_mul_f32 v[58:59], v[58:59], v[70:71]
	v_pk_mul_f32 v[54:55], v[54:55], v[74:75]
	v_pk_mul_f32 v[50:51], v[50:51], v[78:79]
	v_pk_mul_f32 v[48:49], v[48:49], v[76:77]
	v_pk_mul_f32 v[44:45], v[44:45], v[64:65]
	v_pk_mul_f32 v[40:41], v[40:41], v[68:69]
	v_pk_mul_f32 v[36:37], v[36:37], v[72:73]
	v_pk_mul_f32 v[46:47], v[46:47], v[66:67]
	v_pk_mul_f32 v[42:43], v[42:43], v[70:71]
	v_pk_mul_f32 v[38:39], v[38:39], v[74:75]
	v_pk_mul_f32 v[34:35], v[34:35], v[78:79]
	v_pk_mul_f32 v[32:33], v[32:33], v[76:77]
	v_pk_mul_f32 v[28:29], v[28:29], v[64:65]
	v_pk_mul_f32 v[24:25], v[24:25], v[68:69]
	v_pk_mul_f32 v[20:21], v[20:21], v[72:73]
	v_pk_mul_f32 v[30:31], v[30:31], v[66:67]
	v_pk_mul_f32 v[26:27], v[26:27], v[70:71]
	v_pk_mul_f32 v[22:23], v[22:23], v[74:75]
	v_pk_mul_f32 v[18:19], v[18:19], v[78:79]
	v_pk_mul_f32 v[16:17], v[16:17], v[76:77]
	v_pk_mul_f32 v[12:13], v[12:13], v[64:65]
	v_pk_mul_f32 v[8:9], v[8:9], v[68:69]
	v_pk_mul_f32 v[4:5], v[4:5], v[72:73]
	v_pk_mul_f32 v[14:15], v[14:15], v[66:67]
	v_pk_mul_f32 v[10:11], v[10:11], v[70:71]
	v_pk_mul_f32 v[6:7], v[6:7], v[74:75]
	v_pk_mul_f32 v[2:3], v[2:3], v[78:79]
	v_pk_mul_f32 v[0:1], v[0:1], v[76:77]
.LBB0_1035:
	v_exp_f32_e32 v218, v88
	v_exp_f32_e32 v225, v89
	s_add_i32 s0, s75, 1
	s_cmp_lg_u32 s75, 2
	s_cselect_b32 s76, s0, 0
	v_exp_f32_e32 v120, v80
	v_exp_f32_e32 v121, v81
	v_exp_f32_e32 v122, v82
	v_exp_f32_e32 v123, v83
	v_exp_f32_e32 v124, v84
	v_exp_f32_e32 v125, v85
	v_exp_f32_e32 v126, v86
	v_exp_f32_e32 v127, v87
	v_exp_f32_e32 v226, v90
	v_exp_f32_e32 v227, v91
	v_exp_f32_e32 v228, v92
	v_exp_f32_e32 v229, v93
	v_exp_f32_e32 v230, v94
	v_exp_f32_e32 v231, v95
	s_setprio 1
	v_lshl_add_u32 v223, s76, 13, v190
	v_add_u32_e32 v68, v223, v191
	ds_read_b128 v[64:67], v68 offset:49152
	ds_read_b128 v[68:71], v68 offset:53248
	v_add_u32_e32 v116, v223, v192
	ds_read_b128 v[112:115], v116 offset:49152
	ds_read_b128 v[116:119], v116 offset:53248
	s_waitcnt lgkmcnt(0)
	v_mfma_f32_32x32x16_bf16 v[80:95], v[64:67], v[108:111], 0
	v_mfma_f32_32x32x16_bf16 v[64:79], v[68:71], v[108:111], 0
	v_mfma_f32_32x32x16_bf16 v[80:95], v[112:115], v[104:107], v[80:95]
	v_mfma_f32_32x32x16_bf16 v[64:79], v[116:119], v[104:107], v[64:79]
	v_add_u32_e32 v116, v223, v193
	ds_read_b128 v[112:115], v116 offset:49152
	ds_read_b128 v[116:119], v116 offset:53248
	s_waitcnt lgkmcnt(0)
	v_mfma_f32_32x32x16_bf16 v[80:95], v[112:115], v[100:103], v[80:95]
	v_mfma_f32_32x32x16_bf16 v[64:79], v[116:119], v[100:103], v[64:79]
	v_add_u32_e32 v116, v223, v194
	ds_read_b128 v[112:115], v116 offset:49152
	ds_read_b128 v[116:119], v116 offset:53248
	s_waitcnt lgkmcnt(0)
	v_mfma_f32_32x32x16_bf16 v[80:95], v[112:115], v[96:99], v[80:95]
	v_mfma_f32_32x32x16_bf16 v[64:79], v[116:119], v[96:99], v[64:79]
	s_setprio 0
	v_exp_f32_e32 v160, v160
	v_exp_f32_e32 v161, v161
	v_add_f32_e32 v112, v120, v160
	v_add_f32_e32 v113, v121, v161
	v_exp_f32_e32 v162, v162
	v_add_f32_e32 v112, v112, v122
	v_add_f32_e32 v113, v113, v123
	v_exp_f32_e32 v163, v163
	v_add_f32_e32 v112, v112, v162
	v_add_f32_e32 v113, v113, v163
	v_exp_f32_e32 v164, v164
	v_add_f32_e32 v112, v112, v124
	v_add_f32_e32 v113, v113, v125
	v_exp_f32_e32 v165, v165
	v_add_f32_e32 v112, v112, v164
	v_add_f32_e32 v113, v113, v165
	v_exp_f32_e32 v166, v166
	v_add_f32_e32 v112, v112, v126
	v_add_f32_e32 v113, v113, v127
	v_exp_f32_e32 v167, v167
	v_add_f32_e32 v112, v112, v166
	v_add_f32_e32 v113, v113, v167
	v_exp_f32_e32 v168, v168
	v_add_f32_e32 v112, v112, v218
	v_add_f32_e32 v113, v113, v225
	v_exp_f32_e32 v169, v169
	v_add_f32_e32 v112, v112, v168
	v_add_f32_e32 v113, v113, v169
	v_exp_f32_e32 v170, v170
	v_add_f32_e32 v112, v112, v226
	v_add_f32_e32 v113, v113, v227
	v_exp_f32_e32 v171, v171
	v_add_f32_e32 v112, v112, v170
	v_add_f32_e32 v113, v113, v171
	v_exp_f32_e32 v172, v172
	v_add_f32_e32 v112, v112, v228
	v_add_f32_e32 v113, v113, v229
	v_exp_f32_e32 v173, v173
	v_exp_f32_e32 v174, v174
	v_exp_f32_e32 v175, v175
	v_add_f32_e32 v112, v112, v172
	v_add_f32_e32 v113, v113, v173
	s_nop 0
	v_add_f32_e32 v112, v112, v230
	v_add_f32_e32 v113, v113, v231
	s_nop 0
	v_add_f32_e32 v112, v112, v174
	v_add_f32_e32 v113, v113, v175
	s_nop 0
	v_add_f32_e32 v223, v112, v113
	v_cvt_pk_bf16_f32 v112, v120, v121
	v_cvt_pk_bf16_f32 v113, v122, v123
	v_cvt_pk_bf16_f32 v114, v124, v125
	v_cvt_pk_bf16_f32 v115, v126, v127
	v_cvt_pk_bf16_f32 v116, v218, v225
	s_nop 0
	v_mov_b32_e32 v224, v223
	s_nop 1
	v_permlane32_swap_b32_e32 v223, v224
	v_cvt_pk_bf16_f32 v117, v226, v227
	v_cvt_pk_bf16_f32 v118, v228, v229
	v_cvt_pk_bf16_f32 v119, v230, v231
	v_cvt_pk_bf16_f32 v120, v160, v161
	v_cvt_pk_bf16_f32 v121, v162, v163
	v_cvt_pk_bf16_f32 v122, v164, v165
	v_cvt_pk_bf16_f32 v123, v166, v167
	v_cvt_pk_bf16_f32 v124, v168, v169
	v_cvt_pk_bf16_f32 v125, v170, v171
	v_cvt_pk_bf16_f32 v126, v172, v173
	v_cvt_pk_bf16_f32 v127, v174, v175
	v_permlane32_swap_b32_e32 v112, v114
	v_permlane32_swap_b32_e32 v113, v115
	v_permlane32_swap_b32_e32 v116, v118
	v_permlane32_swap_b32_e32 v117, v119
	v_permlane32_swap_b32_e32 v120, v122
	v_permlane32_swap_b32_e32 v121, v123
	v_permlane32_swap_b32_e32 v124, v126
	v_permlane32_swap_b32_e32 v125, v127
	s_lshl_b32 s75, s75, 14
	v_add_u32_e32 v226, s75, v187
	ds_read_b64_tr_b16 v[160:161], v226 offset:0
	ds_read_b64_tr_b16 v[162:163], v226 offset:0x800
	ds_read_b64_tr_b16 v[164:165], v226 offset:0x1000
	ds_read_b64_tr_b16 v[166:167], v226 offset:0x1800
	ds_read_b64_tr_b16 v[168:169], v226 offset:0x2000
	ds_read_b64_tr_b16 v[170:171], v226 offset:0x2800
	ds_read_b64_tr_b16 v[172:173], v226 offset:0x3000
	ds_read_b64_tr_b16 v[174:175], v226 offset:0x3800
	s_setprio 1
	s_waitcnt lgkmcnt(6)
	v_mfma_f32_32x32x16_bf16 v[48:63], v[112:115], v[160:163], v[48:63]
	s_waitcnt lgkmcnt(4)
	v_mfma_f32_32x32x16_bf16 v[48:63], v[116:119], v[164:167], v[48:63]
	s_waitcnt lgkmcnt(2)
	v_mfma_f32_32x32x16_bf16 v[48:63], v[120:123], v[168:171], v[48:63]
	s_waitcnt lgkmcnt(0)
	v_mfma_f32_32x32x16_bf16 v[48:63], v[124:127], v[172:175], v[48:63]
	s_setprio 0
	v_max3_f32 v160, v80, v81, v82
	v_max3_f32 v161, v64, v65, v66
	v_max_f32_e32 v162, v79, v79
	v_max3_f32 v160, v160, v83, v84
	v_max3_f32 v161, v161, v67, v68
	v_max_f32_e32 v163, v95, v95
	v_max3_f32 v160, v160, v85, v86
	v_max3_f32 v161, v161, v69, v70
	v_max_f32_e32 v162, v163, v162
	v_max3_f32 v160, v160, v87, v88
	v_max3_f32 v161, v161, v71, v72
	s_nop 0
	v_max3_f32 v160, v160, v89, v90
	v_max3_f32 v161, v161, v73, v74
	s_nop 0
	v_max3_f32 v160, v160, v91, v92
	v_max3_f32 v161, v161, v75, v76
	s_nop 0
	v_max3_f32 v160, v160, v93, v94
	v_max3_f32 v161, v161, v77, v78
	s_nop 0
	v_max3_f32 v160, v160, v161, v162
	s_nop 0
	v_mov_b32_e32 v161, v160
	s_nop 1
	v_permlane32_swap_b32_e32 v160, v161
	v_max_f32_e32 v161, v161, v161
	v_max_f32_e32 v160, v160, v160
	v_max_f32_e32 v218, v160, v161
	ds_read_b64_tr_b16 v[160:161], v226 offset:0x200
	ds_read_b64_tr_b16 v[162:163], v226 offset:0xa00
	ds_read_b64_tr_b16 v[164:165], v226 offset:0x1200
	ds_read_b64_tr_b16 v[166:167], v226 offset:0x1a00
	ds_read_b64_tr_b16 v[168:169], v226 offset:0x2200
	ds_read_b64_tr_b16 v[170:171], v226 offset:0x2a00
	ds_read_b64_tr_b16 v[172:173], v226 offset:0x3200
	ds_read_b64_tr_b16 v[174:175], v226 offset:0x3a00
	s_setprio 1
	s_waitcnt lgkmcnt(6)
	v_mfma_f32_32x32x16_bf16 v[32:47], v[112:115], v[160:163], v[32:47]
	s_waitcnt lgkmcnt(4)
	v_mfma_f32_32x32x16_bf16 v[32:47], v[116:119], v[164:167], v[32:47]
	s_waitcnt lgkmcnt(2)
	v_mfma_f32_32x32x16_bf16 v[32:47], v[120:123], v[168:171], v[32:47]
	s_waitcnt lgkmcnt(0)
	v_mfma_f32_32x32x16_bf16 v[32:47], v[124:127], v[172:175], v[32:47]
	s_setprio 0
	v_sub_f32_e32 v160, v218, v222
	v_cmp_ge_f32_e32 vcc, s71, v160
	s_cmp_eq_u64 vcc, exec
	v_max_f32_e32 v160, v222, v222
	v_max_f32_e32 v225, v160, v218
	s_cselect_b64 s[0:1], -1, 0
	v_cndmask_b32_e64 v218, v225, v222, s[0:1]
	v_mul_f32_e32 v161, 0xbe38aa3b, v218
	v_fma_f32 v80, v80, v197, v161
	v_fma_f32 v81, v81, v197, v161
	v_fma_f32 v82, v82, v197, v161
	v_fma_f32 v83, v83, v197, v161
	v_fma_f32 v84, v84, v197, v161
	v_fma_f32 v85, v85, v197, v161
	v_fma_f32 v86, v86, v197, v161
	v_fma_f32 v87, v87, v197, v161
	v_fma_f32 v88, v88, v197, v161
	v_fma_f32 v89, v89, v197, v161
	v_fma_f32 v90, v90, v197, v161
	v_fma_f32 v91, v91, v197, v161
	v_fma_f32 v92, v92, v197, v161
	v_fma_f32 v93, v93, v197, v161
	v_fma_f32 v94, v94, v197, v161
	v_fma_f32 v95, v95, v197, v161
	v_fma_f32 v174, v64, v197, v161
	v_fma_f32 v175, v65, v197, v161
	v_fma_f32 v172, v66, v197, v161
	v_fma_f32 v173, v67, v197, v161
	v_fma_f32 v170, v68, v197, v161
	v_fma_f32 v171, v69, v197, v161
	v_fma_f32 v168, v70, v197, v161
	v_fma_f32 v169, v71, v197, v161
	v_fma_f32 v166, v72, v197, v161
	v_fma_f32 v167, v73, v197, v161
	v_fma_f32 v164, v74, v197, v161
	v_fma_f32 v165, v75, v197, v161
	v_fma_f32 v162, v76, v197, v161
	v_fma_f32 v163, v77, v197, v161
	v_fma_f32 v160, v78, v197, v161
	v_fma_f32 v161, v79, v197, v161
	ds_read_b64_tr_b16 v[64:65], v226 offset:0x400
	ds_read_b64_tr_b16 v[66:67], v226 offset:0xc00
	ds_read_b64_tr_b16 v[68:69], v226 offset:0x1400
	ds_read_b64_tr_b16 v[70:71], v226 offset:0x1c00
	ds_read_b64_tr_b16 v[72:73], v226 offset:0x2400
	ds_read_b64_tr_b16 v[74:75], v226 offset:0x2c00
	ds_read_b64_tr_b16 v[76:77], v226 offset:0x3400
	ds_read_b64_tr_b16 v[78:79], v226 offset:0x3c00
	s_setprio 1
	s_waitcnt lgkmcnt(6)
	v_mfma_f32_32x32x16_bf16 v[16:31], v[112:115], v[64:67], v[16:31]
	s_waitcnt lgkmcnt(4)
	v_mfma_f32_32x32x16_bf16 v[16:31], v[116:119], v[68:71], v[16:31]
	s_waitcnt lgkmcnt(2)
	v_mfma_f32_32x32x16_bf16 v[16:31], v[120:123], v[72:75], v[16:31]
	s_waitcnt lgkmcnt(0)
	v_mfma_f32_32x32x16_bf16 v[16:31], v[124:127], v[76:79], v[16:31]
	s_setprio 0
	ds_read_b64_tr_b16 v[64:65], v226 offset:0x600
	ds_read_b64_tr_b16 v[66:67], v226 offset:0xe00
	ds_read_b64_tr_b16 v[68:69], v226 offset:0x1600
	ds_read_b64_tr_b16 v[70:71], v226 offset:0x1e00
	ds_read_b64_tr_b16 v[72:73], v226 offset:0x2600
	ds_read_b64_tr_b16 v[74:75], v226 offset:0x2e00
	ds_read_b64_tr_b16 v[76:77], v226 offset:0x3600
	ds_read_b64_tr_b16 v[78:79], v226 offset:0x3e00
	s_setprio 1
	s_waitcnt lgkmcnt(6)
	v_mfma_f32_32x32x16_bf16 v[0:15], v[112:115], v[64:67], v[0:15]
	s_waitcnt lgkmcnt(4)
	v_mfma_f32_32x32x16_bf16 v[0:15], v[116:119], v[68:71], v[0:15]
	s_waitcnt lgkmcnt(2)
	v_mfma_f32_32x32x16_bf16 v[0:15], v[120:123], v[72:75], v[0:15]
	s_waitcnt lgkmcnt(0)
	v_mfma_f32_32x32x16_bf16 v[0:15], v[124:127], v[76:79], v[0:15]
	s_setprio 0
	s_waitcnt vmcnt(2)
	s_barrier
	s_cmp_gt_u32 s74, 28
	s_cselect_b64 s[48:49], -1, 0
	s_and_b64 vcc, exec, s[48:49]
	s_cbranch_vccnz .LBB0_1037
	s_add_i32 s77, s77, s33
	v_lshl_add_u64 v[64:65], v[176:177], 0, s[14:15]
	s_add_i32 m0, s77, 0xc000
	s_add_i32 s75, s51, s75
	global_load_lds_dwordx4 v[64:65], off
	v_lshl_add_u64 v[64:65], v[178:179], 0, s[34:35]
	s_mov_b32 m0, s75
	s_nop 0
	global_load_lds_dwordx4 v[64:65], off
	v_lshl_add_u64 v[64:65], v[180:181], 0, s[34:35]
	s_add_i32 m0, s75, 0x2000
	s_nop 0
	global_load_lds_dwordx4 v[64:65], off

.LBB0_1050:
	s_lshl_b32 s0, s76, 13
	s_add_i32 s40, s0, 0
	s_setprio 1
	v_add_u32_e32 v112, s40, v189
	v_add_u32_e32 v68, v112, v191
	ds_read_b128 v[64:67], v68 offset:49152
	ds_read_b128 v[68:71], v68 offset:53248
	v_add_u32_e32 v113, v112, v192
	ds_read_b128 v[228:231], v113 offset:49152
	ds_read_b128 v[232:235], v113 offset:53248
	v_add_u32_e32 v113, v112, v193
	s_waitcnt lgkmcnt(0)
	v_mfma_f32_32x32x16_bf16 v[80:95], v[64:67], v[108:111], 0
	v_add_u32_e32 v112, v112, v194
	v_mfma_f32_32x32x16_bf16 v[64:79], v[68:71], v[108:111], 0
	v_mfma_f32_32x32x16_bf16 v[80:95], v[228:231], v[104:107], v[80:95]
	v_mfma_f32_32x32x16_bf16 v[64:79], v[232:235], v[104:107], v[64:79]
	ds_read_b128 v[228:231], v113 offset:49152
	ds_read_b128 v[232:235], v113 offset:53248
	s_waitcnt lgkmcnt(0)
	v_mfma_f32_32x32x16_bf16 v[80:95], v[228:231], v[100:103], v[80:95]
	v_mfma_f32_32x32x16_bf16 v[64:79], v[232:235], v[100:103], v[64:79]
	ds_read_b128 v[228:231], v112 offset:49152
	ds_read_b128 v[232:235], v112 offset:53248
	s_waitcnt lgkmcnt(0)
	v_mfma_f32_32x32x16_bf16 v[80:95], v[228:231], v[96:99], v[80:95]
	v_mfma_f32_32x32x16_bf16 v[64:79], v[232:235], v[96:99], v[64:79]
	s_setprio 0
	v_exp_f32_e32 v163, v180
	v_exp_f32_e32 v164, v181
	v_add_f32_e32 v112, v115, v163
	v_add_f32_e32 v113, v124, v164
	v_exp_f32_e32 v165, v178
	v_add_f32_e32 v112, v112, v125
	v_add_f32_e32 v113, v113, v126
	v_exp_f32_e32 v178, v179
	v_add_f32_e32 v112, v112, v165
	v_add_f32_e32 v113, v113, v178
	v_exp_f32_e32 v176, v176
	v_add_f32_e32 v112, v112, v127
	v_add_f32_e32 v113, v113, v160
	v_exp_f32_e32 v177, v177
	v_add_f32_e32 v112, v112, v176
	v_add_f32_e32 v113, v113, v177
	v_exp_f32_e32 v174, v174
	v_add_f32_e32 v112, v112, v161
	v_add_f32_e32 v113, v113, v162
	v_exp_f32_e32 v175, v175
	v_add_f32_e32 v112, v112, v174
	v_add_f32_e32 v113, v113, v175
	v_exp_f32_e32 v172, v172
	v_add_f32_e32 v112, v112, v116
	v_add_f32_e32 v113, v113, v117
	v_exp_f32_e32 v173, v173
	v_add_f32_e32 v112, v112, v172
	v_add_f32_e32 v113, v113, v173
	v_exp_f32_e32 v170, v170
	v_add_f32_e32 v112, v112, v118
	v_add_f32_e32 v113, v113, v119
	v_exp_f32_e32 v171, v171
	v_add_f32_e32 v112, v112, v170
	v_add_f32_e32 v113, v113, v171
	v_exp_f32_e32 v168, v168
	v_add_f32_e32 v112, v112, v120
	v_add_f32_e32 v113, v113, v121
	v_exp_f32_e32 v169, v169
	v_exp_f32_e32 v166, v166
	v_exp_f32_e32 v167, v167
	v_add_f32_e32 v112, v112, v168
	v_add_f32_e32 v113, v113, v169
	s_nop 0
	v_add_f32_e32 v112, v112, v122
	v_add_f32_e32 v113, v113, v123
	s_nop 0
	v_add_f32_e32 v112, v112, v166
	v_add_f32_e32 v113, v113, v167
	s_nop 0
	v_add_f32_e32 v225, v112, v113
	v_cvt_pk_bf16_f32 v112, v115, v124
	v_cvt_pk_bf16_f32 v113, v125, v126
	v_cvt_pk_bf16_f32 v114, v127, v160
	v_cvt_pk_bf16_f32 v115, v161, v162
	v_cvt_pk_bf16_f32 v116, v116, v117
	s_nop 0
	v_mov_b32_e32 v226, v225
	s_nop 1
	v_permlane32_swap_b32_e32 v225, v226
	v_cvt_pk_bf16_f32 v117, v118, v119
	v_cvt_pk_bf16_f32 v118, v120, v121
	v_cvt_pk_bf16_f32 v119, v122, v123
	v_cvt_pk_bf16_f32 v120, v163, v164
	v_cvt_pk_bf16_f32 v121, v165, v178
	v_cvt_pk_bf16_f32 v122, v176, v177
	v_cvt_pk_bf16_f32 v123, v174, v175
	v_cvt_pk_bf16_f32 v124, v172, v173
	v_cvt_pk_bf16_f32 v125, v170, v171
	v_cvt_pk_bf16_f32 v126, v168, v169
	v_cvt_pk_bf16_f32 v127, v166, v167
	v_permlane32_swap_b32_e32 v112, v114
	v_permlane32_swap_b32_e32 v113, v115
	v_permlane32_swap_b32_e32 v116, v118
	v_permlane32_swap_b32_e32 v117, v119
	v_permlane32_swap_b32_e32 v120, v122
	v_permlane32_swap_b32_e32 v121, v123
	v_permlane32_swap_b32_e32 v124, v126
	v_permlane32_swap_b32_e32 v125, v127
	s_lshl_b32 s0, s36, 14
	v_add_u32_e32 v230, s0, v187
	ds_read_b64_tr_b16 v[160:161], v230 offset:0
	ds_read_b64_tr_b16 v[162:163], v230 offset:0x800
	ds_read_b64_tr_b16 v[164:165], v230 offset:0x1000
	ds_read_b64_tr_b16 v[166:167], v230 offset:0x1800
	ds_read_b64_tr_b16 v[168:169], v230 offset:0x2000
	ds_read_b64_tr_b16 v[170:171], v230 offset:0x2800
	ds_read_b64_tr_b16 v[172:173], v230 offset:0x3000
	ds_read_b64_tr_b16 v[174:175], v230 offset:0x3800
	s_setprio 1
	s_waitcnt lgkmcnt(6)
	v_mfma_f32_32x32x16_bf16 v[48:63], v[112:115], v[160:163], v[48:63]
	s_waitcnt lgkmcnt(4)
	v_mfma_f32_32x32x16_bf16 v[48:63], v[116:119], v[164:167], v[48:63]
	s_waitcnt lgkmcnt(2)
	v_mfma_f32_32x32x16_bf16 v[48:63], v[120:123], v[168:171], v[48:63]
	s_waitcnt lgkmcnt(0)
	v_mfma_f32_32x32x16_bf16 v[48:63], v[124:127], v[172:175], v[48:63]
	s_setprio 0
	v_max3_f32 v160, v80, v81, v82
	v_max3_f32 v161, v64, v65, v66
	v_max_f32_e32 v162, v79, v79
	v_max3_f32 v160, v160, v83, v84
	v_max3_f32 v161, v161, v67, v68
	v_max_f32_e32 v163, v95, v95
	v_max3_f32 v160, v160, v85, v86
	v_max3_f32 v161, v161, v69, v70
	v_max_f32_e32 v162, v163, v162
	v_max3_f32 v160, v160, v87, v88
	v_max3_f32 v161, v161, v71, v72
	s_nop 0
	v_max3_f32 v160, v160, v89, v90
	v_max3_f32 v161, v161, v73, v74
	s_nop 0
	v_max3_f32 v160, v160, v91, v92
	v_max3_f32 v161, v161, v75, v76
	s_nop 0
	v_max3_f32 v160, v160, v93, v94
	v_max3_f32 v161, v161, v77, v78
	s_nop 0
	v_max3_f32 v160, v160, v161, v162
	s_nop 0
	v_mov_b32_e32 v161, v160
	s_nop 1
	v_permlane32_swap_b32_e32 v160, v161
	v_max_f32_e32 v161, v161, v161
	v_max_f32_e32 v160, v160, v160
	v_max_f32_e32 v176, v160, v161
	ds_read_b64_tr_b16 v[160:161], v230 offset:0x200
	ds_read_b64_tr_b16 v[162:163], v230 offset:0xa00
	ds_read_b64_tr_b16 v[164:165], v230 offset:0x1200
	ds_read_b64_tr_b16 v[166:167], v230 offset:0x1a00
	ds_read_b64_tr_b16 v[168:169], v230 offset:0x2200
	ds_read_b64_tr_b16 v[170:171], v230 offset:0x2a00
	ds_read_b64_tr_b16 v[172:173], v230 offset:0x3200
	ds_read_b64_tr_b16 v[174:175], v230 offset:0x3a00
	s_setprio 1
	s_waitcnt lgkmcnt(6)
	v_mfma_f32_32x32x16_bf16 v[32:47], v[112:115], v[160:163], v[32:47]
	s_waitcnt lgkmcnt(4)
	v_mfma_f32_32x32x16_bf16 v[32:47], v[116:119], v[164:167], v[32:47]
	s_waitcnt lgkmcnt(2)
	v_mfma_f32_32x32x16_bf16 v[32:47], v[120:123], v[168:171], v[32:47]
	s_waitcnt lgkmcnt(0)
	v_mfma_f32_32x32x16_bf16 v[32:47], v[124:127], v[172:175], v[32:47]
	s_setprio 0
	v_sub_f32_e32 v160, v176, v227
	v_cmp_ge_f32_e32 vcc, s71, v160
	v_max_f32_e32 v160, v227, v227
	v_max_f32_e32 v160, v160, v176
	v_sub_f32_e32 v161, v227, v160
	v_mul_f32_e32 v161, 0x3e38aa3b, v161
	v_exp_f32_e32 v161, v161
	s_cmp_eq_u64 vcc, exec
	s_cselect_b64 vcc, -1, 0
	v_cndmask_b32_e32 v229, v160, v227, vcc
	v_cndmask_b32_e64 v228, v161, 1.0, vcc
	v_mul_f32_e32 v160, 0xbe38aa3b, v229
	v_fma_f32 v80, v80, v197, v160
	v_fma_f32 v81, v81, v197, v160
	v_fma_f32 v82, v82, v197, v160
	v_fma_f32 v83, v83, v197, v160
	v_fma_f32 v84, v84, v197, v160
	v_fma_f32 v85, v85, v197, v160
	v_fma_f32 v86, v86, v197, v160
	v_fma_f32 v87, v87, v197, v160
	v_fma_f32 v88, v88, v197, v160
	v_fma_f32 v89, v89, v197, v160
	v_fma_f32 v90, v90, v197, v160
	v_fma_f32 v91, v91, v197, v160
	v_fma_f32 v92, v92, v197, v160
	v_fma_f32 v93, v93, v197, v160
	v_fma_f32 v94, v94, v197, v160
	v_fma_f32 v95, v95, v197, v160
	v_fma_f32 v166, v64, v197, v160
	v_fma_f32 v167, v65, v197, v160
	v_fma_f32 v168, v66, v197, v160
	v_fma_f32 v169, v67, v197, v160
	v_fma_f32 v170, v68, v197, v160
	v_fma_f32 v171, v69, v197, v160
	v_fma_f32 v172, v70, v197, v160
	v_fma_f32 v173, v71, v197, v160
	v_fma_f32 v174, v72, v197, v160
	v_fma_f32 v175, v73, v197, v160
	v_fma_f32 v176, v74, v197, v160
	v_fma_f32 v177, v75, v197, v160
	v_fma_f32 v178, v76, v197, v160
	v_fma_f32 v179, v77, v197, v160
	v_fma_f32 v180, v78, v197, v160
	v_fma_f32 v181, v79, v197, v160
	ds_read_b64_tr_b16 v[64:65], v230 offset:0x400
	ds_read_b64_tr_b16 v[66:67], v230 offset:0xc00
	ds_read_b64_tr_b16 v[68:69], v230 offset:0x1400
	ds_read_b64_tr_b16 v[70:71], v230 offset:0x1c00
	ds_read_b64_tr_b16 v[72:73], v230 offset:0x2400
	ds_read_b64_tr_b16 v[74:75], v230 offset:0x2c00
	ds_read_b64_tr_b16 v[76:77], v230 offset:0x3400
	ds_read_b64_tr_b16 v[78:79], v230 offset:0x3c00
	s_setprio 1
	s_waitcnt lgkmcnt(6)
	v_mfma_f32_32x32x16_bf16 v[16:31], v[112:115], v[64:67], v[16:31]
	s_waitcnt lgkmcnt(4)
	v_mfma_f32_32x32x16_bf16 v[16:31], v[116:119], v[68:71], v[16:31]
	s_waitcnt lgkmcnt(2)
	v_mfma_f32_32x32x16_bf16 v[16:31], v[120:123], v[72:75], v[16:31]
	s_waitcnt lgkmcnt(0)
	v_mfma_f32_32x32x16_bf16 v[16:31], v[124:127], v[76:79], v[16:31]
	s_setprio 0
	ds_read_b64_tr_b16 v[64:65], v230 offset:0x600
	ds_read_b64_tr_b16 v[66:67], v230 offset:0xe00
	ds_read_b64_tr_b16 v[68:69], v230 offset:0x1600
	ds_read_b64_tr_b16 v[70:71], v230 offset:0x1e00
	ds_read_b64_tr_b16 v[72:73], v230 offset:0x2600
	ds_read_b64_tr_b16 v[74:75], v230 offset:0x2e00
	ds_read_b64_tr_b16 v[76:77], v230 offset:0x3600
	ds_read_b64_tr_b16 v[78:79], v230 offset:0x3e00
	s_setprio 1
	s_waitcnt lgkmcnt(6)
	v_mfma_f32_32x32x16_bf16 v[0:15], v[112:115], v[64:67], v[0:15]
	s_waitcnt lgkmcnt(4)
	v_mfma_f32_32x32x16_bf16 v[0:15], v[116:119], v[68:71], v[0:15]
	s_waitcnt lgkmcnt(2)
	v_mfma_f32_32x32x16_bf16 v[0:15], v[120:123], v[72:75], v[0:15]
	s_waitcnt lgkmcnt(0)
	v_mfma_f32_32x32x16_bf16 v[0:15], v[124:127], v[76:79], v[0:15]
	s_setprio 0
	s_lshl_b32 s1, s36, 13
	v_lshl_add_u64 v[160:161], s[64:65], 0, v[154:155]
	s_add_i32 s1, s75, s1
	s_waitcnt vmcnt(2)
	s_barrier
	v_lshl_add_u64 v[64:65], v[160:161], 0, s[58:59]
	s_add_i32 m0, s1, 0xc000
	v_lshl_add_u64 v[162:163], s[64:65], 0, v[156:157]
	s_add_i32 s0, s75, s0
	global_load_lds_dwordx4 v[64:65], off
	v_lshl_add_u64 v[64:65], v[162:163], 0, s[10:11]
	s_mov_b32 m0, s0
	v_lshl_add_u64 v[164:165], s[64:65], 0, v[158:159]
	global_load_lds_dwordx4 v[64:65], off
	v_lshl_add_u64 v[64:65], v[164:165], 0, s[10:11]
	s_add_i32 m0, s0, 0x2000
	v_cmp_gt_f32_e32 vcc, 1.0, v228
	global_load_lds_dwordx4 v[64:65], off
	s_cbranch_vccz .LBB0_1054
	s_and_saveexec_b64 s[0:1], s[4:5]
	ds_write_b32 v223, v228 offset:128
	s_or_b64 exec, exec, s[0:1]
	s_waitcnt lgkmcnt(0)
	v_add_u32_e32 v76, s33, v188
	ds_read_b128 v[64:67], v76 offset:224
	ds_read_b128 v[68:71], v76 offset:192
	ds_read_b128 v[72:75], v76 offset:160
	ds_read_b128 v[76:79], v76 offset:128
	s_waitcnt lgkmcnt(0)
	v_pk_mul_f32 v[60:61], v[60:61], v[64:65]
	v_pk_mul_f32 v[56:57], v[56:57], v[68:69]
	v_pk_mul_f32 v[52:53], v[52:53], v[72:73]
	v_pk_mul_f32 v[62:63], v[62:63], v[66:67]
	v_pk_mul_f32 v[58:59], v[58:59], v[70:71]
	v_pk_mul_f32 v[54:55], v[54:55], v[74:75]
	v_pk_mul_f32 v[50:51], v[50:51], v[78:79]
	v_pk_mul_f32 v[48:49], v[48:49], v[76:77]
	v_pk_mul_f32 v[44:45], v[44:45], v[64:65]
	v_pk_mul_f32 v[40:41], v[40:41], v[68:69]
	v_pk_mul_f32 v[36:37], v[36:37], v[72:73]
	v_pk_mul_f32 v[46:47], v[46:47], v[66:67]
	v_pk_mul_f32 v[42:43], v[42:43], v[70:71]
	v_pk_mul_f32 v[38:39], v[38:39], v[74:75]
	v_pk_mul_f32 v[34:35], v[34:35], v[78:79]
	v_pk_mul_f32 v[32:33], v[32:33], v[76:77]
	v_pk_mul_f32 v[28:29], v[28:29], v[64:65]
	v_pk_mul_f32 v[24:25], v[24:25], v[68:69]
	v_pk_mul_f32 v[20:21], v[20:21], v[72:73]
	v_pk_mul_f32 v[30:31], v[30:31], v[66:67]
	v_pk_mul_f32 v[26:27], v[26:27], v[70:71]
	v_pk_mul_f32 v[22:23], v[22:23], v[74:75]
	v_pk_mul_f32 v[18:19], v[18:19], v[78:79]
	v_pk_mul_f32 v[16:17], v[16:17], v[76:77]
	v_pk_mul_f32 v[12:13], v[12:13], v[64:65]
	v_pk_mul_f32 v[8:9], v[8:9], v[68:69]
	v_pk_mul_f32 v[4:5], v[4:5], v[72:73]
	v_pk_mul_f32 v[14:15], v[14:15], v[66:67]
	v_pk_mul_f32 v[10:11], v[10:11], v[70:71]
	v_pk_mul_f32 v[6:7], v[6:7], v[74:75]
	v_pk_mul_f32 v[2:3], v[2:3], v[78:79]
	v_pk_mul_f32 v[0:1], v[0:1], v[76:77]
.LBB0_1054:
	v_exp_f32_e32 v227, v88
	v_exp_f32_e32 v232, v89
	s_add_i32 s0, s76, 1
	s_cmp_lg_u32 s76, 2
	s_cselect_b32 s36, s0, 0
	v_exp_f32_e32 v120, v80
	v_exp_f32_e32 v121, v81
	v_exp_f32_e32 v122, v82
	v_exp_f32_e32 v123, v83
	v_exp_f32_e32 v124, v84
	v_exp_f32_e32 v125, v85
	v_exp_f32_e32 v126, v86
	v_exp_f32_e32 v127, v87
	v_exp_f32_e32 v233, v90
	v_exp_f32_e32 v234, v91
	v_exp_f32_e32 v235, v92
	v_exp_f32_e32 v236, v93
	v_exp_f32_e32 v237, v94
	v_exp_f32_e32 v238, v95
	s_setprio 1
	v_lshl_add_u32 v230, s36, 13, v190
	v_add_u32_e32 v68, v230, v191
	ds_read_b128 v[64:67], v68 offset:49152
	ds_read_b128 v[68:71], v68 offset:53248
	v_add_u32_e32 v116, v230, v192
	ds_read_b128 v[112:115], v116 offset:49152
	ds_read_b128 v[116:119], v116 offset:53248
	s_waitcnt lgkmcnt(0)
	v_mfma_f32_32x32x16_bf16 v[80:95], v[64:67], v[108:111], 0
	v_mfma_f32_32x32x16_bf16 v[64:79], v[68:71], v[108:111], 0
	v_mfma_f32_32x32x16_bf16 v[80:95], v[112:115], v[104:107], v[80:95]
	v_mfma_f32_32x32x16_bf16 v[64:79], v[116:119], v[104:107], v[64:79]
	v_add_u32_e32 v116, v230, v193
	ds_read_b128 v[112:115], v116 offset:49152
	ds_read_b128 v[116:119], v116 offset:53248
	s_waitcnt lgkmcnt(0)
	v_mfma_f32_32x32x16_bf16 v[80:95], v[112:115], v[100:103], v[80:95]
	v_mfma_f32_32x32x16_bf16 v[64:79], v[116:119], v[100:103], v[64:79]
	v_add_u32_e32 v116, v230, v194
	ds_read_b128 v[112:115], v116 offset:49152
	ds_read_b128 v[116:119], v116 offset:53248
	s_waitcnt lgkmcnt(0)
	v_mfma_f32_32x32x16_bf16 v[80:95], v[112:115], v[96:99], v[80:95]
	v_mfma_f32_32x32x16_bf16 v[64:79], v[116:119], v[96:99], v[64:79]
	s_setprio 0
	v_exp_f32_e32 v166, v166
	v_exp_f32_e32 v167, v167
	v_add_f32_e32 v112, v120, v166
	v_add_f32_e32 v113, v121, v167
	v_exp_f32_e32 v168, v168
	v_add_f32_e32 v112, v112, v122
	v_add_f32_e32 v113, v113, v123
	v_exp_f32_e32 v169, v169
	v_add_f32_e32 v112, v112, v168
	v_add_f32_e32 v113, v113, v169
	v_exp_f32_e32 v170, v170
	v_add_f32_e32 v112, v112, v124
	v_add_f32_e32 v113, v113, v125
	v_exp_f32_e32 v171, v171
	v_add_f32_e32 v112, v112, v170
	v_add_f32_e32 v113, v113, v171
	v_exp_f32_e32 v172, v172
	v_add_f32_e32 v112, v112, v126
	v_add_f32_e32 v113, v113, v127
	v_exp_f32_e32 v173, v173
	v_add_f32_e32 v112, v112, v172
	v_add_f32_e32 v113, v113, v173
	v_exp_f32_e32 v174, v174
	v_add_f32_e32 v112, v112, v227
	v_add_f32_e32 v113, v113, v232
	v_exp_f32_e32 v175, v175
	v_add_f32_e32 v112, v112, v174
	v_add_f32_e32 v113, v113, v175
	v_exp_f32_e32 v176, v176
	v_add_f32_e32 v112, v112, v233
	v_add_f32_e32 v113, v113, v234
	v_exp_f32_e32 v177, v177
	v_add_f32_e32 v112, v112, v176
	v_add_f32_e32 v113, v113, v177
	v_exp_f32_e32 v178, v178
	v_add_f32_e32 v112, v112, v235
	v_add_f32_e32 v113, v113, v236
	v_exp_f32_e32 v179, v179
	v_exp_f32_e32 v180, v180
	v_exp_f32_e32 v181, v181
	v_add_f32_e32 v112, v112, v178
	v_add_f32_e32 v113, v113, v179
	s_nop 0
	v_add_f32_e32 v112, v112, v237
	v_add_f32_e32 v113, v113, v238
	s_nop 0
	v_add_f32_e32 v112, v112, v180
	v_add_f32_e32 v113, v113, v181
	s_nop 0
	v_add_f32_e32 v230, v112, v113
	v_cvt_pk_bf16_f32 v112, v120, v121
	v_cvt_pk_bf16_f32 v113, v122, v123
	v_cvt_pk_bf16_f32 v114, v124, v125
	v_cvt_pk_bf16_f32 v115, v126, v127
	v_cvt_pk_bf16_f32 v116, v227, v232
	s_nop 0
	v_mov_b32_e32 v231, v230
	s_nop 1
	v_permlane32_swap_b32_e32 v230, v231
	v_cvt_pk_bf16_f32 v117, v233, v234
	v_cvt_pk_bf16_f32 v118, v235, v236
	v_cvt_pk_bf16_f32 v119, v237, v238
	v_cvt_pk_bf16_f32 v120, v166, v167
	v_cvt_pk_bf16_f32 v121, v168, v169
	v_cvt_pk_bf16_f32 v122, v170, v171
	v_cvt_pk_bf16_f32 v123, v172, v173
	v_cvt_pk_bf16_f32 v124, v174, v175
	v_cvt_pk_bf16_f32 v125, v176, v177
	v_cvt_pk_bf16_f32 v126, v178, v179
	v_cvt_pk_bf16_f32 v127, v180, v181
	v_permlane32_swap_b32_e32 v112, v114
	v_permlane32_swap_b32_e32 v113, v115
	v_permlane32_swap_b32_e32 v116, v118
	v_permlane32_swap_b32_e32 v117, v119
	v_permlane32_swap_b32_e32 v120, v122
	v_permlane32_swap_b32_e32 v121, v123
	v_permlane32_swap_b32_e32 v124, v126
	v_permlane32_swap_b32_e32 v125, v127
	s_lshl_b32 s41, s76, 14
	v_add_u32_e32 v233, s41, v187
	ds_read_b64_tr_b16 v[166:167], v233 offset:0
	ds_read_b64_tr_b16 v[168:169], v233 offset:0x800
	ds_read_b64_tr_b16 v[170:171], v233 offset:0x1000
	ds_read_b64_tr_b16 v[172:173], v233 offset:0x1800
	ds_read_b64_tr_b16 v[174:175], v233 offset:0x2000
	ds_read_b64_tr_b16 v[176:177], v233 offset:0x2800
	ds_read_b64_tr_b16 v[178:179], v233 offset:0x3000
	ds_read_b64_tr_b16 v[180:181], v233 offset:0x3800
	s_setprio 1
	s_waitcnt lgkmcnt(6)
	v_mfma_f32_32x32x16_bf16 v[48:63], v[112:115], v[166:169], v[48:63]
	s_waitcnt lgkmcnt(4)
	v_mfma_f32_32x32x16_bf16 v[48:63], v[116:119], v[170:173], v[48:63]
	s_waitcnt lgkmcnt(2)
	v_mfma_f32_32x32x16_bf16 v[48:63], v[120:123], v[174:177], v[48:63]
	s_waitcnt lgkmcnt(0)
	v_mfma_f32_32x32x16_bf16 v[48:63], v[124:127], v[178:181], v[48:63]
	s_setprio 0
	v_max3_f32 v166, v80, v81, v82
	v_max3_f32 v167, v64, v65, v66
	v_max_f32_e32 v168, v79, v79
	v_max3_f32 v166, v166, v83, v84
	v_max3_f32 v167, v167, v67, v68
	v_max_f32_e32 v169, v95, v95
	v_max3_f32 v166, v166, v85, v86
	v_max3_f32 v167, v167, v69, v70
	v_max_f32_e32 v168, v169, v168
	v_max3_f32 v166, v166, v87, v88
	v_max3_f32 v167, v167, v71, v72
	s_nop 0
	v_max3_f32 v166, v166, v89, v90
	v_max3_f32 v167, v167, v73, v74
	s_nop 0
	v_max3_f32 v166, v166, v91, v92
	v_max3_f32 v167, v167, v75, v76
	s_nop 0
	v_max3_f32 v166, v166, v93, v94
	v_max3_f32 v167, v167, v77, v78
	s_nop 0
	v_max3_f32 v166, v166, v167, v168
	s_nop 0
	v_mov_b32_e32 v167, v166
	s_nop 1
	v_permlane32_swap_b32_e32 v166, v167
	v_max_f32_e32 v167, v167, v167
	v_max_f32_e32 v166, v166, v166
	v_max_f32_e32 v227, v166, v167
	ds_read_b64_tr_b16 v[166:167], v233 offset:0x200
	ds_read_b64_tr_b16 v[168:169], v233 offset:0xa00
	ds_read_b64_tr_b16 v[170:171], v233 offset:0x1200
	ds_read_b64_tr_b16 v[172:173], v233 offset:0x1a00
	ds_read_b64_tr_b16 v[174:175], v233 offset:0x2200
	ds_read_b64_tr_b16 v[176:177], v233 offset:0x2a00
	ds_read_b64_tr_b16 v[178:179], v233 offset:0x3200
	ds_read_b64_tr_b16 v[180:181], v233 offset:0x3a00
	s_setprio 1
	s_waitcnt lgkmcnt(6)
	v_mfma_f32_32x32x16_bf16 v[32:47], v[112:115], v[166:169], v[32:47]
	s_waitcnt lgkmcnt(4)
	v_mfma_f32_32x32x16_bf16 v[32:47], v[116:119], v[170:173], v[32:47]
	s_waitcnt lgkmcnt(2)
	v_mfma_f32_32x32x16_bf16 v[32:47], v[120:123], v[174:177], v[32:47]
	s_waitcnt lgkmcnt(0)
	v_mfma_f32_32x32x16_bf16 v[32:47], v[124:127], v[178:181], v[32:47]
	s_setprio 0
	v_sub_f32_e32 v166, v227, v229
	v_cmp_ge_f32_e32 vcc, s71, v166
	s_cmp_eq_u64 vcc, exec
	v_max_f32_e32 v166, v229, v229
	v_max_f32_e32 v232, v166, v227
	s_cselect_b64 s[0:1], -1, 0
	v_cndmask_b32_e64 v227, v232, v229, s[0:1]
	v_mul_f32_e32 v167, 0xbe38aa3b, v227
	v_fma_f32 v80, v80, v197, v167
	v_fma_f32 v81, v81, v197, v167
	v_fma_f32 v82, v82, v197, v167
	v_fma_f32 v83, v83, v197, v167
	v_fma_f32 v84, v84, v197, v167
	v_fma_f32 v85, v85, v197, v167
	v_fma_f32 v86, v86, v197, v167
	v_fma_f32 v87, v87, v197, v167
	v_fma_f32 v88, v88, v197, v167
	v_fma_f32 v89, v89, v197, v167
	v_fma_f32 v90, v90, v197, v167
	v_fma_f32 v91, v91, v197, v167
	v_fma_f32 v92, v92, v197, v167
	v_fma_f32 v93, v93, v197, v167
	v_fma_f32 v94, v94, v197, v167
	v_fma_f32 v95, v95, v197, v167
	v_fma_f32 v180, v64, v197, v167
	v_fma_f32 v181, v65, v197, v167
	v_fma_f32 v178, v66, v197, v167
	v_fma_f32 v179, v67, v197, v167
	v_fma_f32 v176, v68, v197, v167
	v_fma_f32 v177, v69, v197, v167
	v_fma_f32 v174, v70, v197, v167
	v_fma_f32 v175, v71, v197, v167
	v_fma_f32 v172, v72, v197, v167
	v_fma_f32 v173, v73, v197, v167
	v_fma_f32 v170, v74, v197, v167
	v_fma_f32 v171, v75, v197, v167
	v_fma_f32 v168, v76, v197, v167
	v_fma_f32 v169, v77, v197, v167
	v_fma_f32 v166, v78, v197, v167
	v_fma_f32 v167, v79, v197, v167
	ds_read_b64_tr_b16 v[64:65], v233 offset:0x400
	ds_read_b64_tr_b16 v[66:67], v233 offset:0xc00
	ds_read_b64_tr_b16 v[68:69], v233 offset:0x1400
	ds_read_b64_tr_b16 v[70:71], v233 offset:0x1c00
	ds_read_b64_tr_b16 v[72:73], v233 offset:0x2400
	ds_read_b64_tr_b16 v[74:75], v233 offset:0x2c00
	ds_read_b64_tr_b16 v[76:77], v233 offset:0x3400
	ds_read_b64_tr_b16 v[78:79], v233 offset:0x3c00
	s_setprio 1
	s_waitcnt lgkmcnt(6)
	v_mfma_f32_32x32x16_bf16 v[16:31], v[112:115], v[64:67], v[16:31]
	s_waitcnt lgkmcnt(4)
	v_mfma_f32_32x32x16_bf16 v[16:31], v[116:119], v[68:71], v[16:31]
	s_waitcnt lgkmcnt(2)
	v_mfma_f32_32x32x16_bf16 v[16:31], v[120:123], v[72:75], v[16:31]
	s_waitcnt lgkmcnt(0)
	v_mfma_f32_32x32x16_bf16 v[16:31], v[124:127], v[76:79], v[16:31]
	s_setprio 0
	ds_read_b64_tr_b16 v[64:65], v233 offset:0x600
	ds_read_b64_tr_b16 v[66:67], v233 offset:0xe00
	ds_read_b64_tr_b16 v[68:69], v233 offset:0x1600
	ds_read_b64_tr_b16 v[70:71], v233 offset:0x1e00
	ds_read_b64_tr_b16 v[72:73], v233 offset:0x2600
	ds_read_b64_tr_b16 v[74:75], v233 offset:0x2e00
	ds_read_b64_tr_b16 v[76:77], v233 offset:0x3600
	ds_read_b64_tr_b16 v[78:79], v233 offset:0x3e00
	s_setprio 1
	s_waitcnt lgkmcnt(6)
	v_mfma_f32_32x32x16_bf16 v[0:15], v[112:115], v[64:67], v[0:15]
	s_waitcnt lgkmcnt(4)
	v_mfma_f32_32x32x16_bf16 v[0:15], v[116:119], v[68:71], v[0:15]
	s_waitcnt lgkmcnt(2)
	v_mfma_f32_32x32x16_bf16 v[0:15], v[120:123], v[72:75], v[0:15]
	s_waitcnt lgkmcnt(0)
	v_mfma_f32_32x32x16_bf16 v[0:15], v[124:127], v[76:79], v[0:15]
	s_setprio 0
	s_waitcnt vmcnt(2)
	s_barrier
	s_cmp_gt_u32 s37, 28
	s_cselect_b64 s[38:39], -1, 0
	s_and_b64 vcc, exec, s[38:39]
	s_cbranch_vccnz .LBB0_1056
	s_add_i32 s40, s40, s74
	v_lshl_add_u64 v[64:65], v[160:161], 0, s[60:61]
	s_add_i32 m0, s40, 0xc000
	s_add_i32 s40, s75, s41
	global_load_lds_dwordx4 v[64:65], off
	v_lshl_add_u64 v[64:65], v[162:163], 0, s[34:35]
	s_mov_b32 m0, s40
	s_nop 0
	global_load_lds_dwordx4 v[64:65], off
	v_lshl_add_u64 v[64:65], v[164:165], 0, s[34:35]
	s_add_i32 m0, s40, 0x2000
	s_nop 0
	global_load_lds_dwordx4 v[64:65], off
